# v10 plus last-layer LayerNorm f32-output loop: results into spare quads, next g/b loads issued before the two stores, counted vmcnt leaves stores in flight
# baseline (speedup 1.0000x reference)
.LBB0_1044:
	v_add_co_u32_e32 v54, vcc, 0xfffff000, v50
	global_load_dwordx4 v[68:71], v[50:51], off
	global_load_dwordx4 v[62:65], v[50:51], off offset:-3072
	global_load_dwordx4 v[72:75], v[50:51], off offset:-2048
	global_load_dwordx4 v[76:79], v[50:51], off offset:-1024
	v_addc_co_u32_e32 v55, vcc, -1, v51, vcc
	global_load_dwordx4 v[2:5], v[18:19], off offset:16
	global_load_dwordx4 v[10:13], v[18:19], off
	global_load_dwordx4 v[6:9], v[20:21], off offset:16
	global_load_dwordx4 v[14:17], v[20:21], off
	global_load_dwordx4 v[80:83], v[54:55], off offset:-3072
	global_load_dwordx4 v[84:87], v[54:55], off offset:-2048
	global_load_dwordx4 v[88:91], v[54:55], off offset:-1024
	global_load_dwordx4 v[92:95], v[50:51], off offset:-4096
	s_add_i32 s10, s10, s48
	s_cmp_lt_i32 s10, 0x8000
	v_lshl_add_u64 v[50:51], v[50:51], 0, s[4:5]
	s_waitcnt vmcnt(0)
	v_lshlrev_b32_e32 v128, 16, v68
	v_and_b32_e32 v129, 0xffff0000, v68
	v_lshlrev_b32_e32 v130, 16, v69
	v_and_b32_e32 v131, 0xffff0000, v69
	v_lshlrev_b32_e32 v68, 16, v80
	v_and_b32_e32 v69, 0xffff0000, v80
	v_lshlrev_b32_e32 v132, 16, v70
	v_lshlrev_b32_e32 v136, 16, v94
	v_and_b32_e32 v137, 0xffff0000, v94
	v_add_f32_e32 v94, 0, v68
	v_and_b32_e32 v133, 0xffff0000, v70
	v_lshlrev_b32_e32 v70, 16, v81
	v_add_f32_e32 v94, v94, v69
	v_and_b32_e32 v60, 0xffff0000, v71
	v_lshlrev_b32_e32 v61, 16, v71
	v_and_b32_e32 v71, 0xffff0000, v81
	v_add_f32_e32 v94, v94, v70
	v_lshlrev_b32_e32 v54, 16, v62
	v_and_b32_e32 v55, 0xffff0000, v62
	v_lshlrev_b32_e32 v56, 16, v63
	v_and_b32_e32 v57, 0xffff0000, v63
	v_lshlrev_b32_e32 v58, 16, v64
	v_and_b32_e32 v59, 0xffff0000, v64
	v_lshlrev_b32_e32 v62, 16, v65
	v_and_b32_e32 v63, 0xffff0000, v65
	v_lshlrev_b32_e32 v64, 16, v72
	v_and_b32_e32 v65, 0xffff0000, v72
	v_lshlrev_b32_e32 v66, 16, v73
	v_and_b32_e32 v67, 0xffff0000, v73
	v_lshlrev_b32_e32 v72, 16, v74
	v_and_b32_e32 v73, 0xffff0000, v74
	v_lshlrev_b32_e32 v74, 16, v82
	v_add_f32_e32 v94, v94, v71
	v_lshlrev_b32_e32 v118, 16, v75
	v_and_b32_e32 v119, 0xffff0000, v75
	v_and_b32_e32 v75, 0xffff0000, v82
	v_add_f32_e32 v94, v94, v74
	v_lshlrev_b32_e32 v120, 16, v76
	v_and_b32_e32 v121, 0xffff0000, v76
	v_lshlrev_b32_e32 v76, 16, v83
	v_add_f32_e32 v94, v94, v75
	v_lshlrev_b32_e32 v122, 16, v77
	v_and_b32_e32 v123, 0xffff0000, v77
	v_and_b32_e32 v77, 0xffff0000, v83
	v_add_f32_e32 v94, v94, v76
	v_lshlrev_b32_e32 v124, 16, v78
	v_and_b32_e32 v125, 0xffff0000, v78
	v_lshlrev_b32_e32 v78, 16, v84
	v_add_f32_e32 v94, v94, v77
	v_lshlrev_b32_e32 v126, 16, v79
	v_and_b32_e32 v127, 0xffff0000, v79
	v_and_b32_e32 v79, 0xffff0000, v84
	v_add_f32_e32 v94, v94, v78
	v_lshlrev_b32_e32 v80, 16, v85
	v_add_f32_e32 v94, v94, v79
	v_and_b32_e32 v81, 0xffff0000, v85
	v_add_f32_e32 v94, v94, v80
	v_lshlrev_b32_e32 v82, 16, v86
	v_add_f32_e32 v94, v94, v81
	v_and_b32_e32 v83, 0xffff0000, v86
	v_add_f32_e32 v94, v94, v82
	v_lshlrev_b32_e32 v84, 16, v87
	v_add_f32_e32 v94, v94, v83
	v_and_b32_e32 v85, 0xffff0000, v87
	v_add_f32_e32 v94, v94, v84
	v_lshlrev_b32_e32 v86, 16, v88
	v_add_f32_e32 v94, v94, v85
	v_and_b32_e32 v87, 0xffff0000, v88
	v_add_f32_e32 v94, v94, v86
	v_lshlrev_b32_e32 v88, 16, v89
	v_add_f32_e32 v94, v94, v87
	v_and_b32_e32 v89, 0xffff0000, v89
	v_add_f32_e32 v94, v94, v88
	v_lshlrev_b32_e32 v100, 16, v90
	v_add_f32_e32 v94, v94, v89
	v_and_b32_e32 v101, 0xffff0000, v90
	v_add_f32_e32 v94, v94, v100
	v_lshlrev_b32_e32 v90, 16, v91
	v_add_f32_e32 v94, v94, v101
	v_and_b32_e32 v91, 0xffff0000, v91
	v_add_f32_e32 v94, v94, v90
	v_lshlrev_b32_e32 v134, 16, v92
	v_add_f32_e32 v94, v94, v91
	v_and_b32_e32 v135, 0xffff0000, v92
	v_add_f32_e32 v94, v94, v134
	v_lshlrev_b32_e32 v92, 16, v93
	v_add_f32_e32 v94, v94, v135
	v_and_b32_e32 v93, 0xffff0000, v93
	v_add_f32_e32 v94, v94, v92
	v_add_f32_e32 v94, v94, v93
	v_add_f32_e32 v94, v94, v136
	v_lshlrev_b32_e32 v138, 16, v95
	v_add_f32_e32 v94, v94, v137
	v_and_b32_e32 v139, 0xffff0000, v95
	v_add_f32_e32 v94, v94, v138
	v_add_f32_e32 v94, v94, v139
	v_add_f32_e32 v94, v94, v54
	v_add_f32_e32 v94, v94, v55
	v_add_f32_e32 v94, v94, v56
	v_add_f32_e32 v94, v94, v57
	v_add_f32_e32 v94, v94, v58
	v_add_f32_e32 v94, v94, v59
	v_add_f32_e32 v94, v94, v62
	v_add_f32_e32 v94, v94, v63
	v_add_f32_e32 v94, v94, v64
	v_add_f32_e32 v94, v94, v65
	v_add_f32_e32 v94, v94, v66
	v_add_f32_e32 v94, v94, v67
	v_add_f32_e32 v94, v94, v72
	v_add_f32_e32 v94, v94, v73
	v_add_f32_e32 v94, v94, v118
	v_add_f32_e32 v94, v94, v119
	v_add_f32_e32 v94, v94, v120
	v_add_f32_e32 v94, v94, v121
	v_add_f32_e32 v94, v94, v122
	v_add_f32_e32 v94, v94, v123
	v_add_f32_e32 v94, v94, v124
	v_add_f32_e32 v94, v94, v125
	v_add_f32_e32 v94, v94, v126
	v_add_f32_e32 v94, v94, v127
	v_add_f32_e32 v94, v94, v128
	v_add_f32_e32 v94, v94, v129
	v_add_f32_e32 v94, v94, v130
	v_add_f32_e32 v94, v94, v131
	v_add_f32_e32 v94, v94, v132
	v_add_f32_e32 v94, v94, v133
	v_add_f32_e32 v94, v94, v61
	v_add_f32_e32 v94, v94, v60
	ds_bpermute_b32 v95, v1, v94
	s_waitcnt lgkmcnt(0)
	v_add_f32_e32 v94, v94, v95
	ds_bpermute_b32 v95, v112, v94
	s_waitcnt lgkmcnt(0)
	v_add_f32_e32 v94, v94, v95
	ds_bpermute_b32 v95, v113, v94
	s_waitcnt lgkmcnt(0)
	v_add_f32_e32 v94, v94, v95
	ds_bpermute_b32 v95, v114, v94
	s_waitcnt lgkmcnt(0)
	v_add_f32_e32 v94, v94, v95
	ds_bpermute_b32 v95, v115, v94
	s_waitcnt lgkmcnt(0)
	v_add_f32_e32 v94, v94, v95
	ds_bpermute_b32 v95, v116, v94
	s_waitcnt lgkmcnt(0)
	v_add_f32_e32 v94, v94, v95
	v_mul_f32_e32 v96, 0x39800000, v94
	v_pk_add_f32 v[140:141], v[68:69], v[96:97] op_sel_hi:[1,0] neg_lo:[0,1] neg_hi:[0,1]
	v_pk_add_f32 v[142:143], v[70:71], v[96:97] op_sel_hi:[1,0] neg_lo:[0,1] neg_hi:[0,1]
	v_pk_add_f32 v[70:71], v[72:73], v[96:97] op_sel_hi:[1,0] neg_lo:[0,1] neg_hi:[0,1]
	v_pk_add_f32 v[72:73], v[118:119], v[96:97] op_sel_hi:[1,0] neg_lo:[0,1] neg_hi:[0,1]
	v_pk_mul_f32 v[118:119], v[140:141], v[140:141]
	v_pk_add_f32 v[144:145], v[74:75], v[96:97] op_sel_hi:[1,0] neg_lo:[0,1] neg_hi:[0,1]
	v_pk_add_f32 v[146:147], v[76:77], v[96:97] op_sel_hi:[1,0] neg_lo:[0,1] neg_hi:[0,1]
	v_pk_add_f32 v[108:109], v[78:79], v[96:97] op_sel_hi:[1,0] neg_lo:[0,1] neg_hi:[0,1]
	v_pk_add_f32 v[110:111], v[80:81], v[96:97] op_sel_hi:[1,0] neg_lo:[0,1] neg_hi:[0,1]
	v_pk_add_f32 v[104:105], v[82:83], v[96:97] op_sel_hi:[1,0] neg_lo:[0,1] neg_hi:[0,1]
	v_pk_add_f32 v[106:107], v[84:85], v[96:97] op_sel_hi:[1,0] neg_lo:[0,1] neg_hi:[0,1]
	v_pk_add_f32 v[98:99], v[86:87], v[96:97] op_sel_hi:[1,0] neg_lo:[0,1] neg_hi:[0,1]
	v_pk_add_f32 v[102:103], v[88:89], v[96:97] op_sel_hi:[1,0] neg_lo:[0,1] neg_hi:[0,1]
	v_pk_add_f32 v[94:95], v[100:101], v[96:97] op_sel_hi:[1,0] neg_lo:[0,1] neg_hi:[0,1]
	v_pk_add_f32 v[100:101], v[90:91], v[96:97] op_sel_hi:[1,0] neg_lo:[0,1] neg_hi:[0,1]
	v_pk_add_f32 v[90:91], v[134:135], v[96:97] op_sel_hi:[1,0] neg_lo:[0,1] neg_hi:[0,1]
	v_pk_add_f32 v[92:93], v[92:93], v[96:97] op_sel_hi:[1,0] neg_lo:[0,1] neg_hi:[0,1]
	v_pk_add_f32 v[86:87], v[136:137], v[96:97] op_sel_hi:[1,0] neg_lo:[0,1] neg_hi:[0,1]
	v_pk_add_f32 v[88:89], v[138:139], v[96:97] op_sel_hi:[1,0] neg_lo:[0,1] neg_hi:[0,1]
	v_pk_add_f32 v[82:83], v[54:55], v[96:97] op_sel_hi:[1,0] neg_lo:[0,1] neg_hi:[0,1]
	v_pk_add_f32 v[84:85], v[56:57], v[96:97] op_sel_hi:[1,0] neg_lo:[0,1] neg_hi:[0,1]
	v_pk_add_f32 v[78:79], v[58:59], v[96:97] op_sel_hi:[1,0] neg_lo:[0,1] neg_hi:[0,1]
	v_pk_add_f32 v[80:81], v[62:63], v[96:97] op_sel_hi:[1,0] neg_lo:[0,1] neg_hi:[0,1]
	v_pk_add_f32 v[74:75], v[64:65], v[96:97] op_sel_hi:[1,0] neg_lo:[0,1] neg_hi:[0,1]
	v_pk_add_f32 v[76:77], v[66:67], v[96:97] op_sel_hi:[1,0] neg_lo:[0,1] neg_hi:[0,1]
	v_pk_add_f32 v[64:65], v[120:121], v[96:97] op_sel_hi:[1,0] neg_lo:[0,1] neg_hi:[0,1]
	v_pk_add_f32 v[68:69], v[122:123], v[96:97] op_sel_hi:[1,0] neg_lo:[0,1] neg_hi:[0,1]
	v_pk_add_f32 v[62:63], v[124:125], v[96:97] op_sel_hi:[1,0] neg_lo:[0,1] neg_hi:[0,1]
	v_pk_add_f32 v[66:67], v[126:127], v[96:97] op_sel_hi:[1,0] neg_lo:[0,1] neg_hi:[0,1]
	v_pk_add_f32 v[54:55], v[128:129], v[96:97] op_sel_hi:[1,0] neg_lo:[0,1] neg_hi:[0,1]
	v_pk_add_f32 v[56:57], v[130:131], v[96:97] op_sel_hi:[1,0] neg_lo:[0,1] neg_hi:[0,1]
	v_pk_add_f32 v[58:59], v[132:133], v[96:97] op_sel_hi:[1,0] neg_lo:[0,1] neg_hi:[0,1]
	v_pk_add_f32 v[60:61], v[60:61], v[96:97] op_sel_hi:[1,0] neg_lo:[0,1] neg_hi:[0,1]
	v_pk_mul_f32 v[120:121], v[142:143], v[142:143]
	v_add_f32_e32 v96, v118, v119
	v_add_f32_e32 v96, v120, v96
	v_pk_mul_f32 v[122:123], v[144:145], v[144:145]
	v_add_f32_e32 v96, v121, v96
	v_add_f32_e32 v96, v122, v96
	v_pk_mul_f32 v[124:125], v[146:147], v[146:147]
	v_add_f32_e32 v96, v123, v96
	v_add_f32_e32 v96, v124, v96
	v_pk_mul_f32 v[126:127], v[108:109], v[108:109]
	v_add_f32_e32 v96, v125, v96
	v_add_f32_e32 v96, v126, v96
	v_pk_mul_f32 v[128:129], v[110:111], v[110:111]
	v_add_f32_e32 v96, v127, v96
	v_add_f32_e32 v96, v128, v96
	v_pk_mul_f32 v[130:131], v[104:105], v[104:105]
	v_add_f32_e32 v96, v129, v96
	v_add_f32_e32 v96, v130, v96
	v_pk_mul_f32 v[132:133], v[106:107], v[106:107]
	v_add_f32_e32 v96, v131, v96
	v_add_f32_e32 v96, v132, v96
	v_pk_mul_f32 v[134:135], v[98:99], v[98:99]
	v_add_f32_e32 v96, v133, v96
	v_add_f32_e32 v96, v134, v96
	v_pk_mul_f32 v[136:137], v[102:103], v[102:103]
	v_add_f32_e32 v96, v135, v96
	v_add_f32_e32 v96, v136, v96
	v_pk_mul_f32 v[138:139], v[94:95], v[94:95]
	v_add_f32_e32 v96, v137, v96
	v_add_f32_e32 v96, v138, v96
	v_pk_mul_f32 v[148:149], v[100:101], v[100:101]
	v_add_f32_e32 v96, v139, v96
	v_add_f32_e32 v96, v148, v96
	v_pk_mul_f32 v[150:151], v[90:91], v[90:91]
	v_add_f32_e32 v96, v149, v96
	v_add_f32_e32 v96, v150, v96
	v_pk_mul_f32 v[152:153], v[92:93], v[92:93]
	v_add_f32_e32 v96, v151, v96
	v_add_f32_e32 v96, v152, v96
	v_pk_mul_f32 v[154:155], v[86:87], v[86:87]
	v_add_f32_e32 v96, v153, v96
	v_add_f32_e32 v96, v154, v96
	v_pk_mul_f32 v[156:157], v[88:89], v[88:89]
	v_add_f32_e32 v96, v155, v96
	v_add_f32_e32 v96, v156, v96
	v_pk_mul_f32 v[158:159], v[82:83], v[82:83]
	v_add_f32_e32 v96, v157, v96
	v_add_f32_e32 v96, v158, v96
	v_pk_mul_f32 v[160:161], v[84:85], v[84:85]
	v_add_f32_e32 v96, v159, v96
	v_add_f32_e32 v96, v160, v96
	v_pk_mul_f32 v[162:163], v[78:79], v[78:79]
	v_add_f32_e32 v96, v161, v96
	v_add_f32_e32 v96, v162, v96
	v_pk_mul_f32 v[164:165], v[80:81], v[80:81]
	v_add_f32_e32 v96, v163, v96
	v_add_f32_e32 v96, v164, v96
	v_pk_mul_f32 v[166:167], v[74:75], v[74:75]
	v_add_f32_e32 v96, v165, v96
	v_add_f32_e32 v96, v166, v96
	v_pk_mul_f32 v[168:169], v[76:77], v[76:77]
	v_add_f32_e32 v96, v167, v96
	v_add_f32_e32 v96, v168, v96
	v_pk_mul_f32 v[170:171], v[70:71], v[70:71]
	v_add_f32_e32 v96, v169, v96
	v_add_f32_e32 v96, v170, v96
	v_pk_mul_f32 v[172:173], v[72:73], v[72:73]
	v_add_f32_e32 v96, v171, v96
	v_add_f32_e32 v96, v172, v96
	v_pk_mul_f32 v[174:175], v[64:65], v[64:65]
	v_add_f32_e32 v96, v173, v96
	v_add_f32_e32 v96, v174, v96
	v_pk_mul_f32 v[176:177], v[68:69], v[68:69]
	v_add_f32_e32 v96, v175, v96
	v_add_f32_e32 v96, v176, v96
	v_pk_mul_f32 v[178:179], v[62:63], v[62:63]
	v_add_f32_e32 v96, v177, v96
	v_add_f32_e32 v96, v178, v96
	v_pk_mul_f32 v[180:181], v[66:67], v[66:67]
	v_add_f32_e32 v96, v179, v96
	v_add_f32_e32 v96, v180, v96
	v_pk_mul_f32 v[182:183], v[54:55], v[54:55]
	v_add_f32_e32 v96, v181, v96
	v_add_f32_e32 v96, v182, v96
	v_pk_mul_f32 v[184:185], v[56:57], v[56:57]
	v_add_f32_e32 v96, v183, v96
	v_add_f32_e32 v96, v184, v96
	v_pk_mul_f32 v[186:187], v[58:59], v[58:59]
	v_add_f32_e32 v96, v185, v96
	v_add_f32_e32 v96, v186, v96
	v_pk_mul_f32 v[188:189], v[60:61], v[60:61]
	v_add_f32_e32 v96, v187, v96
	v_add_f32_e32 v96, v189, v96
	v_add_f32_e32 v96, v188, v96
	ds_bpermute_b32 v117, v1, v96
	s_waitcnt lgkmcnt(0)
	v_add_f32_e32 v96, v96, v117
	ds_bpermute_b32 v117, v112, v96
	s_waitcnt lgkmcnt(0)
	v_add_f32_e32 v96, v96, v117
	ds_bpermute_b32 v117, v113, v96
	s_waitcnt lgkmcnt(0)
	v_add_f32_e32 v96, v96, v117
	ds_bpermute_b32 v117, v114, v96
	s_waitcnt lgkmcnt(0)
	v_add_f32_e32 v96, v96, v117
	ds_bpermute_b32 v117, v115, v96
	s_waitcnt lgkmcnt(0)
	v_add_f32_e32 v96, v96, v117
	ds_bpermute_b32 v117, v116, v96
	s_waitcnt lgkmcnt(0)
	v_add_f32_e32 v96, v96, v117
	v_fmamk_f32 v96, v96, 0x39800000, v237
	v_mul_f32_e32 v117, 0x4f800000, v96
	v_cmp_gt_f32_e32 vcc, s62, v96
	s_nop 1
	v_cndmask_b32_e32 v96, v96, v117, vcc
	v_sqrt_f32_e32 v117, v96
	s_nop 0
	v_add_u32_e32 v118, -1, v117
	v_add_u32_e32 v119, 1, v117
	v_fma_f32 v120, -v118, v117, v96
	v_fma_f32 v121, -v119, v117, v96
	v_cmp_ge_f32_e64 s[40:41], 0, v120
	s_nop 1
	v_cndmask_b32_e64 v117, v117, v118, s[40:41]
	v_cmp_lt_f32_e64 s[40:41], 0, v121
	s_nop 1
	v_cndmask_b32_e64 v117, v117, v119, s[40:41]
	v_mul_f32_e32 v118, 0x37800000, v117
	v_cndmask_b32_e32 v117, v117, v118, vcc
	v_cmp_class_f32_e32 vcc, v96, v238
	s_nop 1
	v_cndmask_b32_e32 v96, v117, v96, vcc
	v_div_scale_f32 v117, s[12:13], v96, v96, 1.0
	v_rcp_f32_e32 v119, v117
	v_div_scale_f32 v118, vcc, 1.0, v96, 1.0
	v_fma_f32 v120, -v117, v119, 1.0
	v_fmac_f32_e32 v119, v120, v119
	v_mul_f32_e32 v120, v118, v119
	v_fma_f32 v121, -v117, v120, v118
	v_fmac_f32_e32 v120, v121, v119
	v_fma_f32 v117, -v117, v120, v118
	v_div_fmas_f32 v117, v117, v119, v120
	v_div_fixup_f32 v96, v117, v96, 1.0
	v_pk_mul_f32 v[118:119], v[140:141], v[96:97] op_sel_hi:[1,0]
	v_pk_mul_f32 v[120:121], v[142:143], v[96:97] op_sel_hi:[1,0]
	v_pk_mul_f32 v[122:123], v[144:145], v[96:97] op_sel_hi:[1,0]
	v_pk_mul_f32 v[124:125], v[146:147], v[96:97] op_sel_hi:[1,0]
	v_pk_fma_f32 v[246:247], v[12:13], v[120:121], v[16:17]
	v_pk_fma_f32 v[244:245], v[10:11], v[118:119], v[14:15]
	v_pk_fma_f32 v[250:251], v[4:5], v[124:125], v[8:9]
	v_pk_fma_f32 v[248:249], v[2:3], v[122:123], v[6:7]
	global_load_dwordx4 v[2:5], v[24:25], off
	global_load_dwordx4 v[6:9], v[22:23], off
	global_load_dwordx4 v[10:13], v[22:23], off offset:16
	global_load_dwordx4 v[14:17], v[24:25], off offset:16
	global_store_dwordx4 v[52:53], v[244:247], off
	global_store_dwordx4 v[52:53], v[248:251], off offset:16
	s_nop 0
	v_pk_mul_f32 v[110:111], v[110:111], v[96:97] op_sel_hi:[1,0]
	v_pk_mul_f32 v[108:109], v[108:109], v[96:97] op_sel_hi:[1,0]
	v_pk_mul_f32 v[106:107], v[106:107], v[96:97] op_sel_hi:[1,0]
	v_pk_mul_f32 v[104:105], v[104:105], v[96:97] op_sel_hi:[1,0]
	v_pk_mul_f32 v[102:103], v[102:103], v[96:97] op_sel_hi:[1,0]
	v_pk_mul_f32 v[98:99], v[98:99], v[96:97] op_sel_hi:[1,0]
	v_pk_mul_f32 v[100:101], v[100:101], v[96:97] op_sel_hi:[1,0]
	v_pk_mul_f32 v[94:95], v[94:95], v[96:97] op_sel_hi:[1,0]
	v_pk_mul_f32 v[92:93], v[92:93], v[96:97] op_sel_hi:[1,0]
	v_pk_mul_f32 v[90:91], v[90:91], v[96:97] op_sel_hi:[1,0]
	v_pk_mul_f32 v[88:89], v[88:89], v[96:97] op_sel_hi:[1,0]
	v_pk_mul_f32 v[86:87], v[86:87], v[96:97] op_sel_hi:[1,0]
	v_pk_mul_f32 v[84:85], v[84:85], v[96:97] op_sel_hi:[1,0]
	v_pk_mul_f32 v[82:83], v[82:83], v[96:97] op_sel_hi:[1,0]
	v_pk_mul_f32 v[80:81], v[80:81], v[96:97] op_sel_hi:[1,0]
	v_pk_mul_f32 v[78:79], v[78:79], v[96:97] op_sel_hi:[1,0]
	v_pk_mul_f32 v[76:77], v[76:77], v[96:97] op_sel_hi:[1,0]
	v_pk_mul_f32 v[74:75], v[74:75], v[96:97] op_sel_hi:[1,0]
	v_pk_mul_f32 v[72:73], v[72:73], v[96:97] op_sel_hi:[1,0]
	v_pk_mul_f32 v[70:71], v[70:71], v[96:97] op_sel_hi:[1,0]
	v_pk_mul_f32 v[68:69], v[68:69], v[96:97] op_sel_hi:[1,0]
	v_pk_mul_f32 v[64:65], v[64:65], v[96:97] op_sel_hi:[1,0]
	v_pk_mul_f32 v[66:67], v[66:67], v[96:97] op_sel_hi:[1,0]
	v_pk_mul_f32 v[62:63], v[62:63], v[96:97] op_sel_hi:[1,0]
	v_pk_mul_f32 v[58:59], v[58:59], v[96:97] op_sel_hi:[1,0]
	v_pk_mul_f32 v[60:61], v[60:61], v[96:97] op_sel_hi:[1,0]
	v_pk_mul_f32 v[56:57], v[56:57], v[96:97] op_sel_hi:[1,0]
	v_pk_mul_f32 v[54:55], v[54:55], v[96:97] op_sel_hi:[1,0]
	s_waitcnt vmcnt(4)
	v_pk_fma_f32 v[244:245], v[6:7], v[108:109], v[2:3]
	v_pk_fma_f32 v[246:247], v[8:9], v[110:111], v[4:5]
	s_waitcnt vmcnt(2)
	v_pk_fma_f32 v[248:249], v[10:11], v[104:105], v[14:15]
	v_pk_fma_f32 v[250:251], v[12:13], v[106:107], v[16:17]
	global_load_dwordx4 v[2:5], v[28:29], off
	global_load_dwordx4 v[6:9], v[26:27], off
	global_load_dwordx4 v[10:13], v[26:27], off offset:16
	global_load_dwordx4 v[14:17], v[28:29], off offset:16
	global_store_dwordx4 v[52:53], v[244:247], off offset:2048
	global_store_dwordx4 v[52:53], v[248:251], off offset:2064
	s_nop 0
	v_add_co_u32_e32 v104, vcc, s59, v52
	s_waitcnt vmcnt(4)
	v_pk_fma_f32 v[244:245], v[6:7], v[98:99], v[2:3]
	v_addc_co_u32_e32 v105, vcc, 0, v53, vcc
	v_add_co_u32_e32 v106, vcc, s55, v52
	v_pk_fma_f32 v[246:247], v[8:9], v[102:103], v[4:5]
	s_nop 0
	v_addc_co_u32_e32 v107, vcc, 0, v53, vcc
	s_waitcnt vmcnt(2)
	v_pk_fma_f32 v[248:249], v[10:11], v[94:95], v[14:15]
	v_pk_fma_f32 v[250:251], v[12:13], v[100:101], v[16:17]
	global_load_dwordx4 v[2:5], v[32:33], off
	global_load_dwordx4 v[6:9], v[30:31], off
	global_load_dwordx4 v[10:13], v[30:31], off offset:16
	global_load_dwordx4 v[14:17], v[32:33], off offset:16
	global_store_dwordx4 v[106:107], v[244:247], off offset:-4096
	global_store_dwordx4 v[104:105], v[248:251], off offset:16
	s_nop 0
	s_waitcnt vmcnt(4)
	v_pk_fma_f32 v[244:245], v[6:7], v[90:91], v[2:3]
	v_pk_fma_f32 v[246:247], v[8:9], v[92:93], v[4:5]
	s_waitcnt vmcnt(2)
	v_pk_fma_f32 v[248:249], v[10:11], v[86:87], v[14:15]
	v_pk_fma_f32 v[250:251], v[12:13], v[88:89], v[16:17]
	global_load_dwordx4 v[2:5], v[36:37], off
	global_load_dwordx4 v[6:9], v[34:35], off
	global_load_dwordx4 v[10:13], v[34:35], off offset:16
	global_load_dwordx4 v[14:17], v[36:37], off offset:16
	global_store_dwordx4 v[104:105], v[244:247], off offset:2048
	global_store_dwordx4 v[104:105], v[248:251], off offset:2064
	s_nop 0
	s_waitcnt vmcnt(4)
	v_pk_fma_f32 v[244:245], v[6:7], v[82:83], v[2:3]
	v_pk_fma_f32 v[246:247], v[8:9], v[84:85], v[4:5]
	s_waitcnt vmcnt(2)
	v_pk_fma_f32 v[248:249], v[10:11], v[78:79], v[14:15]
	v_pk_fma_f32 v[250:251], v[12:13], v[80:81], v[16:17]
	global_load_dwordx4 v[2:5], v[40:41], off
	global_load_dwordx4 v[6:9], v[38:39], off
	global_load_dwordx4 v[10:13], v[38:39], off offset:16
	global_load_dwordx4 v[14:17], v[40:41], off offset:16
	global_store_dwordx4 v[106:107], v[244:247], off
	global_store_dwordx4 v[106:107], v[248:251], off offset:16
	s_nop 0
	s_waitcnt vmcnt(4)
	v_pk_fma_f32 v[244:245], v[6:7], v[74:75], v[2:3]
	v_pk_fma_f32 v[246:247], v[8:9], v[76:77], v[4:5]
	s_waitcnt vmcnt(2)
	v_pk_fma_f32 v[248:249], v[10:11], v[70:71], v[14:15]
	v_pk_fma_f32 v[250:251], v[12:13], v[72:73], v[16:17]
	global_load_dwordx4 v[2:5], v[44:45], off
	global_load_dwordx4 v[6:9], v[42:43], off
	global_load_dwordx4 v[10:13], v[42:43], off offset:16
	global_load_dwordx4 v[14:17], v[44:45], off offset:16
	global_store_dwordx4 v[106:107], v[244:247], off offset:2048
	global_store_dwordx4 v[106:107], v[248:251], off offset:2064
	s_nop 0
	v_add_co_u32_e32 v70, vcc, s90, v52
	s_waitcnt vmcnt(4)
	v_pk_fma_f32 v[244:245], v[6:7], v[64:65], v[2:3]
	v_addc_co_u32_e32 v71, vcc, 0, v53, vcc
	v_pk_fma_f32 v[246:247], v[8:9], v[68:69], v[4:5]
	s_waitcnt vmcnt(2)
	v_pk_fma_f32 v[248:249], v[10:11], v[62:63], v[14:15]
	v_pk_fma_f32 v[250:251], v[12:13], v[66:67], v[16:17]
	global_load_dwordx4 v[2:5], v[48:49], off offset:16
	global_load_dwordx4 v[6:9], v[46:47], off offset:16
	global_load_dwordx4 v[10:13], v[46:47], off
	global_load_dwordx4 v[14:17], v[48:49], off
	global_store_dwordx4 v[70:71], v[244:247], off
	global_store_dwordx4 v[70:71], v[248:251], off offset:16
	s_nop 0
	v_lshl_add_u64 v[52:53], v[52:53], 0, s[22:23]
	s_waitcnt vmcnt(4)
	v_pk_fma_f32 v[2:3], v[6:7], v[58:59], v[2:3]
	v_pk_fma_f32 v[4:5], v[8:9], v[60:61], v[4:5] op_sel:[0,1,0] op_sel_hi:[1,0,1]
	s_waitcnt vmcnt(2)
	v_pk_fma_f32 v[6:7], v[10:11], v[54:55], v[14:15]
	v_pk_fma_f32 v[8:9], v[12:13], v[56:57], v[16:17]
	global_store_dwordx4 v[70:71], v[6:9], off offset:2048
	global_store_dwordx4 v[70:71], v[2:5], off offset:2064
	s_cbranch_scc1 .LBB0_1044
